# attention unit: gate values prefetched at unit head into an LDS slot (3 exposed global loads per unit removed)
# speedup vs baseline: 1.0152x; 1.0067x over previous
.LBB0_1179:
	s_or_b64 exec, exec, s[2:3]
	v_mbcnt_lo_u32_b32 v247, -1, 0
	v_mbcnt_hi_u32_b32 v247, -1, v247
	ds_read2st64_b32 v[40:41], v1 offset1:1
	v_readlane_b32 s0, v255, 58
	v_lshlrev_b64 v[36:37], 11, v[36:37]
	v_readlane_b32 s1, v255, 59
	s_waitcnt lgkmcnt(0)
	v_lshlrev_b32_e32 v43, 16, v41
	v_lshlrev_b32_e32 v42, 16, v40
	v_and_b32_e32 v41, 0xffff0000, v41
	v_and_b32_e32 v40, 0xffff0000, v40
	v_pk_fma_f32 v[4:5], v[4:5], v[2:3], v[40:41] op_sel_hi:[1,0,1]
	ds_read2st64_b32 v[40:41], v1 offset0:2 offset1:3
	v_pk_fma_f32 v[20:21], v[20:21], v[2:3], v[42:43] op_sel_hi:[1,0,1]
	v_lshl_add_u64 v[36:37], s[0:1], 0, v[36:37]
	v_cvt_pk_bf16_f32 v4, v4, v5
	v_readlane_b32 s0, v255, 42
	s_waitcnt lgkmcnt(0)
	v_lshlrev_b32_e32 v43, 16, v41
	v_lshlrev_b32_e32 v42, 16, v40
	v_and_b32_e32 v41, 0xffff0000, v41
	v_and_b32_e32 v40, 0xffff0000, v40
	v_pk_fma_f32 v[6:7], v[6:7], v[2:3], v[40:41] op_sel_hi:[1,0,1]
	ds_read2st64_b32 v[40:41], v1 offset0:4 offset1:5
	v_pk_fma_f32 v[22:23], v[22:23], v[2:3], v[42:43] op_sel_hi:[1,0,1]
	v_cvt_pk_bf16_f32 v5, v6, v7
	s_add_i32 s36, s36, s0
	v_cvt_pk_bf16_f32 v20, v20, v21
	s_waitcnt lgkmcnt(0)
	v_lshlrev_b32_e32 v43, 16, v41
	v_lshlrev_b32_e32 v42, 16, v40
	v_and_b32_e32 v41, 0xffff0000, v41
	v_and_b32_e32 v40, 0xffff0000, v40
	v_pk_fma_f32 v[8:9], v[8:9], v[2:3], v[40:41] op_sel_hi:[1,0,1]
	ds_read2st64_b32 v[40:41], v1 offset0:6 offset1:7
	v_pk_fma_f32 v[24:25], v[24:25], v[2:3], v[42:43] op_sel_hi:[1,0,1]
	v_cvt_pk_bf16_f32 v21, v22, v23
	s_cmpk_gt_i32 s36, 0x3ff
	s_waitcnt lgkmcnt(0)
	v_lshlrev_b32_e32 v43, 16, v41
	v_lshlrev_b32_e32 v42, 16, v40
	v_and_b32_e32 v41, 0xffff0000, v41
	v_and_b32_e32 v40, 0xffff0000, v40
	v_pk_fma_f32 v[10:11], v[10:11], v[2:3], v[40:41] op_sel_hi:[1,0,1]
	ds_read2st64_b32 v[40:41], v1 offset0:8 offset1:9
	v_pk_fma_f32 v[26:27], v[26:27], v[2:3], v[42:43] op_sel_hi:[1,0,1]
	s_waitcnt lgkmcnt(0)
	v_lshlrev_b32_e32 v43, 16, v41
	v_lshlrev_b32_e32 v42, 16, v40
	v_and_b32_e32 v41, 0xffff0000, v41
	v_and_b32_e32 v40, 0xffff0000, v40
	v_pk_fma_f32 v[12:13], v[12:13], v[2:3], v[40:41] op_sel_hi:[1,0,1]
	ds_read2st64_b32 v[40:41], v1 offset0:10 offset1:11
	v_pk_fma_f32 v[28:29], v[28:29], v[2:3], v[42:43] op_sel_hi:[1,0,1]
	s_waitcnt lgkmcnt(0)
	v_lshlrev_b32_e32 v43, 16, v41
	v_lshlrev_b32_e32 v42, 16, v40
	v_and_b32_e32 v41, 0xffff0000, v41
	v_and_b32_e32 v40, 0xffff0000, v40
	v_pk_fma_f32 v[14:15], v[14:15], v[2:3], v[40:41] op_sel_hi:[1,0,1]
	ds_read2st64_b32 v[40:41], v1 offset0:12 offset1:13
	v_pk_fma_f32 v[30:31], v[30:31], v[2:3], v[42:43] op_sel_hi:[1,0,1]
	s_waitcnt lgkmcnt(0)
	v_lshlrev_b32_e32 v43, 16, v41
	v_lshlrev_b32_e32 v42, 16, v40
	v_and_b32_e32 v41, 0xffff0000, v41
	v_and_b32_e32 v40, 0xffff0000, v40
	v_pk_fma_f32 v[16:17], v[16:17], v[2:3], v[40:41] op_sel_hi:[1,0,1]
	ds_read2st64_b32 v[40:41], v1 offset0:14 offset1:15
	v_pk_fma_f32 v[32:33], v[32:33], v[2:3], v[42:43] op_sel_hi:[1,0,1]
	s_waitcnt lgkmcnt(0)
	v_lshlrev_b32_e32 v43, 16, v41
	v_lshlrev_b32_e32 v42, 16, v40
	v_and_b32_e32 v41, 0xffff0000, v41
	v_and_b32_e32 v40, 0xffff0000, v40
	v_pk_fma_f32 v[34:35], v[34:35], v[2:3], v[42:43] op_sel_hi:[1,0,1]
	v_pk_fma_f32 v[18:19], v[18:19], v[2:3], v[40:41] op_sel_hi:[1,0,1]
	v_lshlrev_b32_e32 v2, 7, v38
	v_lshl_add_u64 v[36:37], v[36:37], 0, v[2:3]
	v_lshlrev_b32_e32 v2, 3, v135
	v_lshl_add_u64 v[36:37], v[36:37], 0, v[2:3]
	global_store_dwordx2 v[36:37], v[4:5], off offset:64
	v_cvt_pk_bf16_f32 v4, v24, v25
	v_cvt_pk_bf16_f32 v5, v26, v27
	global_store_dwordx2 v[36:37], v[4:5], off offset:16
	v_cvt_pk_bf16_f32 v4, v8, v9
	v_cvt_pk_bf16_f32 v5, v10, v11
	global_store_dwordx2 v[36:37], v[4:5], off offset:80
	v_cvt_pk_bf16_f32 v4, v28, v29
	v_cvt_pk_bf16_f32 v5, v30, v31
	global_store_dwordx2 v[36:37], v[4:5], off offset:32
	v_cvt_pk_bf16_f32 v4, v12, v13
	v_cvt_pk_bf16_f32 v5, v14, v15
	global_store_dwordx2 v[36:37], v[4:5], off offset:96
	v_cvt_pk_bf16_f32 v4, v32, v33
	v_cvt_pk_bf16_f32 v5, v34, v35
	global_store_dwordx2 v[36:37], v[4:5], off offset:48
	v_cvt_pk_bf16_f32 v4, v16, v17
	v_cvt_pk_bf16_f32 v5, v18, v19
	global_store_dwordx2 v[36:37], v[20:21], off
	global_store_dwordx2 v[36:37], v[4:5], off offset:112
	s_barrier
	s_cbranch_scc1 .LBB0_1402
.LBB0_1180:
	s_lshr_b32 s1, s36, 1
	s_ashr_i32 s0, s36, 8
	s_and_b32 s1, s1, 0x7c
	s_add_i32 s2, s1, s0
	s_ashr_i32 s3, s2, 31
	s_getpc_b64 s[0:1]
	s_add_u32 s0, s0, _ZL6NSA_QB@rel32@lo+4
	s_addc_u32 s1, s1, _ZL6NSA_QB@rel32@hi+12
	s_add_u32 s0, s0, s2
	s_addc_u32 s1, s1, s3
	global_load_ubyte v1, v3, s[0:1]
	v_mov_b32_e32 v156, v0
	s_and_b32 s0, s36, 3
	v_readfirstlane_b32 s1, v156
	s_ashr_i32 s17, s1, 6
	s_lshl_b32 s46, s17, 3
	s_waitcnt vmcnt(0)
	v_bfe_u32 v76, v156, 2, 3
	v_or_b32_e32 v154, s46, v76
	s_bfe_u32 s8, s36, 0x10002
	s_lshl_b32 s1, s0, 2
	v_writelane_b32 v255, s1, 41
	s_lshl_b32 s12, s8, 13
	v_readlane_b32 s2, v255, 52
	v_readlane_b32 s3, v255, 53
	s_lshl_b32 s9, s0, 6
	v_ashrrev_i32_e32 v77, 3, v156
	v_bfe_u32 v5, v156, 5, 1
	v_cmp_lt_i32_e32 vcc, -1, v77
	v_lshlrev_b32_e32 v204, 4, v5
	v_mov_b32_e32 v205, v3
	v_lshlrev_b32_e32 v4, 3, v156
	v_and_b32_e32 v4, 56, v4
	v_and_b32_e32 v10, 31, v156
	s_mov_b32 s24, 1
	v_and_b32_e32 v157, 63, v156
	s_mov_b32 s25, 0
	v_add_u32_e32 v79, 0x80, v77
	v_mov_b32_e32 v36, 0
	s_mov_b32 s27, 0
	v_mov_b32_e32 v80, 0
	s_waitcnt vmcnt(0)
	v_readfirstlane_b32 s20, v1
	s_lshl_b32 s21, s20, 6
	v_add_u32_e32 v112, s21, v154
	v_ashrrev_i32_e32 v113, 31, v112
	v_and_b32_e32 v1, 3, v156
	v_lshl_add_u64 v[146:147], s[12:13], 0, v[112:113]
	v_or_b32_e32 v155, s1, v1
	v_lshlrev_b64 v[6:7], 11, v[146:147]
	s_add_i32 s1, s21, s46
	v_lshl_add_u64 v[6:7], s[2:3], 0, v[6:7]
	s_sub_i32 s1, s1, 31
	s_lshl_b32 s2, s8, 18
	v_readlane_b32 s3, v255, 50
	s_add_u32 s4, s3, s2
	v_readlane_b32 s3, v255, 51
	s_addc_u32 s5, s3, 0
	s_lshr_b32 s10, s20, 4
	s_ashr_i32 s11, s1, 4
	v_readlane_b32 s1, v255, 48
	s_add_u32 s1, s1, s2
	v_readlane_b32 s2, v255, 49
	v_lshlrev_b32_e32 v2, 7, v155
	s_addc_u32 s3, s2, 0
	s_lshl_b32 s0, s0, 7
	v_lshl_add_u64 v[6:7], v[6:7], 0, v[2:3]
	v_subrev_u32_e32 v2, 31, v112
	s_add_u32 s2, s1, s0
	v_ashrrev_i32_e32 v143, 4, v2
	s_addc_u32 s3, s3, 0
	v_min_u32_e32 v2, 0x1ff, v77
	s_add_u32 s6, s4, s0
	v_lshlrev_b32_e32 v2, 8, v2
	s_addc_u32 s7, s5, 0
	s_add_i32 s0, s10, 2
	v_cndmask_b32_e32 v2, 0, v2, vcc
	v_lshl_add_u64 v[6:7], v[6:7], 0, v[204:205]
	s_lshr_b32 s16, s0, 1
	v_lshlrev_b32_e32 v2, 1, v2
	v_readlane_b32 vcc_lo, v255, 60
	v_readlane_b32 vcc_hi, v255, 61
	v_mul_u32_u24_e32 v94, 3, v155
	v_mov_b32_e32 v95, 0xc0
	v_lshlrev_b32_e32 v94, 2, v94
	v_mov_b64_e32 v[92:93], vcc
	v_mad_i64_i32 v[92:93], vcc, v146, v95, v[92:93]
	v_mov_b32_e32 v95, 0
	v_lshlrev_b32_e32 v247, 4, v156
	v_lshl_add_u64 v[92:93], v[92:93], 0, v[94:95]
	v_add_u32_e32 v247, 0x1d400, v247
	global_load_dwordx3 v[94:96], v[92:93], off
	global_load_dwordx4 v[114:117], v[6:7], off
	global_load_dwordx4 v[118:121], v[6:7], off offset:32
	global_load_dwordx4 v[122:125], v[6:7], off offset:64
	global_load_dwordx4 v[126:129], v[6:7], off offset:96
	s_add_u32 s22, s2, 0x8000
	v_lshl_add_u64 v[8:9], s[2:3], 0, v[2:3]
	v_lshlrev_b32_e32 v6, 1, v4
	v_mov_b32_e32 v7, v3
	s_addc_u32 s23, s3, 0
	v_lshl_add_u64 v[8:9], v[8:9], 0, v[6:7]
	global_load_dwordx4 v[70:73], v[8:9], off
	v_lshl_add_u64 v[8:9], s[22:23], 0, v[2:3]
	v_lshl_add_u64 v[8:9], v[8:9], 0, v[6:7]
	global_load_dwordx4 v[12:15], v[8:9], off
	v_lshlrev_b32_e32 v147, 4, v156
	v_mul_lo_u32 v8, v77, s97
	v_and_b32_e32 v9, 0x70, v147
	v_add3_u32 v142, 0, v8, v9
	v_mul_u32_u24_e32 v205, 0x90, v10
	v_mad_u64_u32 v[148:149], s[0:1], v77, 48, v[142:143]
	v_add_u32_e32 v37, 0x4800, v142
	v_lshl_add_u64 v[144:145], s[2:3], 0, v[6:7]
	v_lshl_add_u64 v[74:75], s[6:7], 0, v[2:3]
	v_add3_u32 v158, 0, v205, v204
	v_lshlrev_b32_e32 v113, 2, v5
	v_add_u32_e32 v78, 0x4800, v148
	s_lshl_b32 s26, s16, 7
	v_lshlrev_b32_e32 v2, 1, v4
	s_waitcnt vmcnt(1)
	ds_write_b128 v142, v[70:73]
	s_waitcnt vmcnt(0)
	ds_write_b128 v142, v[12:15] offset:18432
	ds_write_b96 v247, v[94:96]
	s_waitcnt lgkmcnt(0)
	s_barrier
	s_branch .LBB0_1183

.LBB0_1318:
	s_or_b64 exec, exec, s[6:7]
	v_lshlrev_b32_e32 v36, 5, v156
	s_lshl_b32 s0, s17, 12
	v_and_b32_e32 v36, 0x60, v36
	v_mul_lo_u32 v38, v37, s97
	s_add_i32 s0, s0, 0
	v_add3_u32 v206, 0, v38, v36
	v_lshl_add_u32 v1, v157, 2, s0
	v_mad_u64_u32 v[208:209], s[0:1], v37, 48, v[206:207]
	s_lshl_b32 s0, s17, 7
	s_add_i32 s0, s64, s0
	s_waitcnt lgkmcnt(0)
	s_barrier
	s_waitcnt vmcnt(2)
	ds_write_b128 v206, v[134:137]
	ds_write_b128 v206, v[130:133] offset:16
	s_waitcnt vmcnt(0)
	ds_write_b128 v208, v[142:145] offset:36864
	ds_write_b128 v208, v[138:141] offset:36880
	v_mov_b32_e32 v36, s0
	ds_read_b128 v[38:41], v36
	ds_read_b128 v[42:45], v36 offset:16
	ds_read_b128 v[46:49], v36 offset:32
	ds_read_b128 v[50:53], v36 offset:48
	s_movk_i32 s0, 0xc0
	v_add_u32_e32 v1, 0x15000, v1
	s_waitcnt lgkmcnt(2)
	v_or_b32_e32 v38, v42, v38
	v_or_b32_e32 v39, v43, v39
	v_or_b32_e32 v40, v44, v40
	v_or_b32_e32 v41, v45, v41
	s_waitcnt lgkmcnt(1)
	v_or_b32_e32 v38, v38, v46
	v_or_b32_e32 v39, v39, v47
	v_or_b32_e32 v40, v40, v48
	v_or_b32_e32 v41, v41, v49
	s_waitcnt lgkmcnt(0)
	v_or_b32_e32 v42, v38, v50
	v_or_b32_e32 v43, v39, v51
	v_or_b32_e32 v44, v40, v52
	v_or_b32_e32 v45, v41, v53
	ds_read_b128 v[38:41], v36 offset:64
	v_lshl_add_u64 v[210:211], s[22:23], 0, v[2:3]
	v_or_b32_e32 v2, s21, v113
	v_lshl_add_u32 v209, v154, 4, s64
	s_and_b32 s31, s20, 0xfe
	s_waitcnt lgkmcnt(0)
	v_or_b32_e32 v42, v42, v38
	v_or_b32_e32 v43, v43, v39
	v_or_b32_e32 v44, v44, v40
	v_or_b32_e32 v45, v45, v41
	ds_read_b128 v[38:41], v36 offset:80
	v_add_u32_e32 v246, 0x80, v37
	s_lshr_b32 s17, s20, 1
	v_cmp_le_i32_e64 s[38:39], v113, v154
	v_cmp_lt_i32_e64 s[42:43], v113, v154
	s_waitcnt lgkmcnt(0)
	v_or_b32_e32 v42, v42, v38
	v_or_b32_e32 v43, v43, v39
	v_or_b32_e32 v44, v44, v40
	v_or_b32_e32 v45, v45, v41
	ds_read_b128 v[38:41], v36 offset:96
	s_add_i32 s31, s31, 2
	s_mov_b32 s22, 0
	v_mov_b32_e32 v243, 0
	s_mov_b32 s9, 0
	s_waitcnt lgkmcnt(0)
	v_or_b32_e32 v42, v42, v38
	v_or_b32_e32 v43, v43, v39
	v_or_b32_e32 v44, v44, v40
	v_or_b32_e32 v45, v45, v41
	ds_read_b128 v[38:41], v36 offset:112
	s_waitcnt lgkmcnt(0)
	v_or_b32_e32 v36, v42, v38
	v_or_b32_e32 v42, v43, v39
	v_or_b32_e32 v38, v44, v40
	v_or_b32_e32 v39, v45, v41
	v_readfirstlane_b32 s37, v36
	v_readfirstlane_b32 s33, v42
	ds_read_b32 v36, v247
	v_mov_b32_e32 v40, v4
	v_mov_b32_e32 v41, v20
	v_mov_b32_e32 v20, v5
	v_readfirstlane_b32 s16, v39
	v_readfirstlane_b32 s8, v38
	s_waitcnt lgkmcnt(0)
	v_pk_mul_f32 v[40:41], v[40:41], v[36:37] op_sel_hi:[1,0]
	v_pk_mul_f32 v[4:5], v[20:21], v[36:37] op_sel_hi:[1,0]
	v_cvt_pk_bf16_f32 v40, v40, v41
	v_cvt_pk_bf16_f32 v4, v4, v5
	ds_write2st64_b32 v1, v40, v4 offset1:1
	v_mov_b32_e32 v4, v6
	v_mov_b32_e32 v5, v22
	v_pk_mul_f32 v[4:5], v[4:5], v[36:37] op_sel_hi:[1,0]
	v_mov_b32_e32 v22, v7
	v_cvt_pk_bf16_f32 v6, v4, v5
	v_pk_mul_f32 v[4:5], v[22:23], v[36:37] op_sel_hi:[1,0]
	v_mov_b32_e32 v7, v3
	v_cvt_pk_bf16_f32 v4, v4, v5
	ds_write2st64_b32 v1, v6, v4 offset0:2 offset1:3
	v_mov_b32_e32 v4, v8
	v_mov_b32_e32 v5, v24
	v_pk_mul_f32 v[4:5], v[4:5], v[36:37] op_sel_hi:[1,0]
	v_mov_b32_e32 v24, v9
	v_cvt_pk_bf16_f32 v6, v4, v5
	v_pk_mul_f32 v[4:5], v[24:25], v[36:37] op_sel_hi:[1,0]
	v_mov_b32_e32 v8, v3
	v_cvt_pk_bf16_f32 v4, v4, v5
	ds_write2st64_b32 v1, v6, v4 offset0:4 offset1:5
	v_mov_b32_e32 v4, v10
	v_mov_b32_e32 v5, v26
	v_pk_mul_f32 v[4:5], v[4:5], v[36:37] op_sel_hi:[1,0]
	v_mov_b32_e32 v26, v11
	v_cvt_pk_bf16_f32 v6, v4, v5
	v_pk_mul_f32 v[4:5], v[26:27], v[36:37] op_sel_hi:[1,0]
	v_mov_b32_e32 v9, v3
	v_cvt_pk_bf16_f32 v4, v4, v5
	ds_write2st64_b32 v1, v6, v4 offset0:6 offset1:7
	v_mov_b32_e32 v4, v12
	v_mov_b32_e32 v5, v28
	v_pk_mul_f32 v[4:5], v[4:5], v[36:37] op_sel_hi:[1,0]
	v_mov_b32_e32 v28, v13
	v_cvt_pk_bf16_f32 v6, v4, v5
	v_pk_mul_f32 v[4:5], v[28:29], v[36:37] op_sel_hi:[1,0]
	v_mov_b32_e32 v10, v3
	v_cvt_pk_bf16_f32 v4, v4, v5
	ds_write2st64_b32 v1, v6, v4 offset0:8 offset1:9
	v_mov_b32_e32 v4, v14
	v_mov_b32_e32 v5, v30
	v_pk_mul_f32 v[4:5], v[4:5], v[36:37] op_sel_hi:[1,0]
	v_mov_b32_e32 v30, v15
	v_cvt_pk_bf16_f32 v6, v4, v5
	v_pk_mul_f32 v[4:5], v[30:31], v[36:37] op_sel_hi:[1,0]
	v_mov_b32_e32 v11, v3
	v_cvt_pk_bf16_f32 v4, v4, v5
	ds_write2st64_b32 v1, v6, v4 offset0:10 offset1:11
	v_mov_b32_e32 v4, v16
	v_mov_b32_e32 v5, v32
	v_pk_mul_f32 v[4:5], v[4:5], v[36:37] op_sel_hi:[1,0]
	v_mov_b32_e32 v32, v17
	v_cvt_pk_bf16_f32 v6, v4, v5
	v_pk_mul_f32 v[4:5], v[32:33], v[36:37] op_sel_hi:[1,0]
	v_mov_b32_e32 v16, v3
	v_cvt_pk_bf16_f32 v4, v4, v5
	ds_write2st64_b32 v1, v6, v4 offset0:12 offset1:13
	v_mov_b32_e32 v4, v18
	v_mov_b32_e32 v5, v34
	v_pk_mul_f32 v[4:5], v[4:5], v[36:37] op_sel_hi:[1,0]
	v_mov_b32_e32 v34, v19
	v_cvt_pk_bf16_f32 v6, v4, v5
	v_pk_mul_f32 v[4:5], v[34:35], v[36:37] op_sel_hi:[1,0]
	v_mov_b32_e32 v17, v3
	v_cvt_pk_bf16_f32 v4, v4, v5
	ds_write2st64_b32 v1, v6, v4 offset0:14 offset1:15
	v_or_b32_e32 v4, 32, v2
	v_cmp_gt_i32_e64 s[40:41], v4, v112
	v_or_b32_e32 v4, 33, v2
	v_cmp_gt_i32_e64 s[44:45], v4, v112
	v_or_b32_e32 v4, 2, v2
	v_cmp_le_i32_e64 s[46:47], v4, v112
	v_or_b32_e32 v4, 34, v2
	v_cmp_gt_i32_e64 s[48:49], v4, v112
	v_or_b32_e32 v4, 3, v2
	v_cmp_le_i32_e64 s[50:51], v4, v112
	v_or_b32_e32 v4, 35, v2
	v_cmp_gt_i32_e64 s[52:53], v4, v112
	v_or_b32_e32 v4, 8, v2
	v_cmp_le_i32_e64 s[54:55], v4, v112
	v_or_b32_e32 v4, 40, v2
	v_cmp_gt_i32_e64 s[56:57], v4, v112
	v_or_b32_e32 v4, 9, v2
	v_cmp_le_i32_e64 s[58:59], v4, v112
	v_or_b32_e32 v4, 41, v2
	v_cmp_gt_i32_e64 s[60:61], v4, v112
	v_or_b32_e32 v4, 10, v2
	v_cmp_le_i32_e64 s[62:63], v4, v112
	v_or_b32_e32 v4, 42, v2
	v_cmp_gt_i32_e64 s[64:65], v4, v112
	v_or_b32_e32 v4, 11, v2
	v_cmp_le_i32_e64 s[66:67], v4, v112
	v_or_b32_e32 v4, 43, v2
	v_cmp_gt_i32_e64 s[68:69], v4, v112
	v_or_b32_e32 v4, 16, v2
	v_cmp_le_i32_e64 s[70:71], v4, v112
	v_or_b32_e32 v4, 48, v2
	v_cmp_gt_i32_e64 s[72:73], v4, v112
	v_or_b32_e32 v4, 17, v2
	v_cmp_le_i32_e64 s[74:75], v4, v112
	v_or_b32_e32 v4, 49, v2
	v_cmp_gt_i32_e64 s[76:77], v4, v112
	v_or_b32_e32 v4, 18, v2
	v_cmp_le_i32_e64 s[78:79], v4, v112
	v_or_b32_e32 v4, 50, v2
	v_cmp_gt_i32_e64 s[80:81], v4, v112
	v_or_b32_e32 v4, 19, v2
	v_cmp_le_i32_e64 s[82:83], v4, v112
	v_or_b32_e32 v4, 51, v2
	v_cmp_gt_i32_e64 s[84:85], v4, v112
	v_or_b32_e32 v4, 24, v2
	v_cmp_le_i32_e64 s[86:87], v4, v112
	v_or_b32_e32 v4, 56, v2
	v_cmp_gt_i32_e64 s[88:89], v4, v112
	v_or_b32_e32 v4, 25, v2
	v_cmp_le_i32_e64 s[90:91], v4, v112
	v_or_b32_e32 v4, 57, v2
	v_cmp_gt_i32_e64 s[92:93], v4, v112
	v_or_b32_e32 v4, 26, v2
	v_cmp_le_i32_e64 s[94:95], v4, v112
	v_or_b32_e32 v4, 58, v2
	v_cmp_gt_i32_e64 s[96:97], v4, v112
	v_or_b32_e32 v4, 27, v2
	v_or_b32_e32 v2, 59, v2
	v_cmp_le_i32_e64 s[2:3], v4, v112
	v_cmp_gt_i32_e64 s[4:5], v2, v112
	v_mov_b32_e32 v2, v3
	v_mov_b32_e32 v4, v3
	v_mov_b32_e32 v5, v3
	v_mov_b32_e32 v6, v3
	v_mov_b32_e32 v12, v3
	v_mov_b32_e32 v13, v3
	v_mov_b32_e32 v14, v3
	v_mov_b32_e32 v15, v3
	v_mov_b64_e32 v[32:33], v[16:17]
	v_mov_b64_e32 v[48:49], v[16:17]
	v_mov_b64_e32 v[30:31], v[14:15]
	v_mov_b64_e32 v[28:29], v[12:13]
	v_mov_b64_e32 v[26:27], v[10:11]
	v_mov_b64_e32 v[24:25], v[8:9]
	v_mov_b64_e32 v[22:23], v[6:7]
	v_mov_b64_e32 v[20:21], v[4:5]
	v_mov_b64_e32 v[18:19], v[2:3]
	v_mov_b64_e32 v[46:47], v[14:15]
	v_mov_b64_e32 v[44:45], v[12:13]
	v_mov_b64_e32 v[42:43], v[10:11]
	v_mov_b64_e32 v[40:41], v[8:9]
	v_mov_b64_e32 v[38:39], v[6:7]
	v_mov_b64_e32 v[36:37], v[4:5]
	v_mov_b64_e32 v[34:35], v[2:3]
	v_mov_b32_e32 v2, 0
	s_waitcnt lgkmcnt(0)
	s_barrier
	s_cmp_lt_u32 s9, s17
	s_cselect_b64 s[24:25], -1, 0
	s_cmp_ge_u32 s9, s17
	s_cbranch_scc1 .LBB0_1321
	s_branch .LBB0_1320

.Lsel_exit:
	v_mov_b32_e32 v2, v252
	s_nop 1
	v_permlane32_swap_b32_e32 v252, v2
	v_mov_b32_e32 v5, v0
	v_add_f32_e32 v4, v252, v2
	v_mov_b32_e32 v2, 0
	v_readfirstlane_b32 s0, v5
	v_cmp_lt_f32_e32 vcc, 0, v4
	s_and_saveexec_b64 s[2:3], vcc
	v_readlane_b32 s48, v255, 60
	v_readlane_b32 s49, v255, 61
	v_readlane_b32 s23, v255, 41
	s_cbranch_execz .LBB0_1363
	s_add_i32 s1, s12, s21
	s_ashr_i32 s0, s0, 3
	v_lshrrev_b32_e32 v2, 2, v5
	s_and_b32 s0, s0, -8
	v_and_or_b32 v2, v2, 7, s1
	v_add_u32_e32 v2, s0, v2
	ds_read_b32 v2, v247 offset:4
	s_waitcnt lgkmcnt(0)
	v_div_scale_f32 v5, s[0:1], v4, v4, v2
	v_rcp_f32_e32 v6, v5
	v_div_scale_f32 v7, vcc, v2, v4, v2
	v_fma_f32 v8, -v5, v6, 1.0
	v_fmac_f32_e32 v6, v8, v6
	v_mul_f32_e32 v8, v7, v6
	v_fma_f32 v9, -v5, v8, v7
	v_fmac_f32_e32 v8, v9, v6
	v_fma_f32 v5, -v5, v8, v7
	v_div_fmas_f32 v5, v5, v6, v8
	v_div_fixup_f32 v2, v5, v4, v2

.LBB0_1400:
	v_mov_b32_e32 v2, v179
	s_nop 1
	v_permlane32_swap_b32_e32 v179, v2
	v_and_or_b32 v38, v113, 3, s23
	v_ashrrev_i32_e32 v113, 31, v112
	v_add_f32_e32 v39, v179, v2
	v_lshl_add_u64 v[36:37], s[12:13], 0, v[112:113]
	v_mov_b32_e32 v2, 0
	v_cmp_lt_f32_e32 vcc, 0, v39
	s_and_saveexec_b64 s[2:3], vcc
	s_cbranch_execz .LBB0_1179
	ds_read_b32 v2, v247 offset:8
	s_waitcnt lgkmcnt(0)
	v_div_scale_f32 v40, s[0:1], v39, v39, v2
	v_rcp_f32_e32 v41, v40
	v_div_scale_f32 v42, vcc, v2, v39, v2
	v_fma_f32 v43, -v40, v41, 1.0
	v_fmac_f32_e32 v41, v43, v41
	v_mul_f32_e32 v43, v42, v41
	v_fma_f32 v44, -v40, v43, v42
	v_fmac_f32_e32 v43, v44, v41
	v_fma_f32 v40, -v40, v43, v42
	v_div_fmas_f32 v40, v40, v41, v43
	v_div_fixup_f32 v2, v40, v39, v2
	s_branch .LBB0_1179
